# combined + leaders skip the L2 write-back at seams 3-5 when row-block groups are co-located + waves 1-7 touch the next phase's first weight K-tiles before the rendezvous
# baseline (speedup 1.0000x reference)
; __device__ __forceinline__ unsigned xb_ld(unsigned* p)              { return __hip_atomic_load(p, __ATOMIC_RELAXED, __HIP_MEMORY_SCOPE_AGENT); }
; __device__ __forceinline__ unsigned xb_add(unsigned* p, unsigned v) { return __hip_atomic_fetch_add(p, v, __ATOMIC_RELAXED, __HIP_MEMORY_SCOPE_AGENT); }
; #define XB_SPIN(cond, bar) do { unsigned _sp = 0; while (cond) { __builtin_amdgcn_s_sleep(1); \
;     if ((++_sp & 255u) == 0u) { if (xb_ld(&(bar)[XB_TMO])) break; if (_sp > XB_SPIN_CAP) { atomicAdd(&(bar)[XB_TMO], 1u); break; } } } } while (0)
; __device__ __forceinline__ void xcd_barrier(const XcdBarrier& b) {
;     asm volatile("s_waitcnt vmcnt(0)" ::: "memory");
;     __syncthreads();
;     if (threadIdx.x == 0) {
;         unsigned* bar = b.bar;
;         __builtin_amdgcn_s_waitcnt(0);
;         unsigned nloc = b.st[0], nx = b.st[1];
;         if (nloc == 0u) { xcd_barrier_complete(bar, b.x, nloc, nx); b.st[0] = nloc; b.st[1] = nx; }
;         const unsigned old = xb_add(&bar[XB_XSUB(b.x)], 1u);
;         const unsigned gen = old / nloc;
;         if (old + 1u == (gen + 1u) * nloc) {
;             __builtin_amdgcn_fence(__ATOMIC_RELEASE, "agent");
;             asm volatile("s_waitcnt vmcnt(0)" ::: "memory");
;             const unsigned og = xb_add(&bar[XB_TOP], 1u);
;             const unsigned tg = og / nx;
;             if (og + 1u == (tg + 1u) * nx) xb_add(&bar[XB_TOPGEN], 1u);
;             else XB_SPIN(xb_ld(&bar[XB_TOPGEN]) == tg, bar);
;             __builtin_amdgcn_fence(__ATOMIC_ACQUIRE, "agent");
;             xb_add(&bar[XB_XGEN(b.x)], 1u);
;             asm volatile("s_waitcnt vmcnt(0)" ::: "memory");
;         } else {
;             XB_SPIN(xb_ld(&bar[XB_XGEN(b.x)]) == gen, bar);
;             __builtin_amdgcn_fence(__ATOMIC_ACQUIRE, "agent");
;             asm volatile("s_waitcnt vmcnt(0)" ::: "memory");
;         }
.Lmy_bpf_3:
	s_mov_b64 s[0:1], exec
	v_readlane_b32 s4, v254, 9
	v_readlane_b32 s5, v254, 10
	s_and_b64 s[4:5], s[0:1], s[4:5]
	s_mov_b64 exec, s[4:5]
	s_cbranch_execz .LBB0_861
	s_cmp_eq_u32 s74, 3
	s_cbranch_scc1 .Lmy_fb_3_orig
	s_add_i32 s4, 0, 0x26700
	v_mov_b32_e32 v0, s4
	ds_read2_b32 v[2:3], v0 offset1:1
	ds_read_b32 v9, v0 offset:8
	s_lshl_b32 s4, s88, 8
	s_add_u32 s4, s72, s4
	s_addc_u32 s5, s73, 0
	v_mov_b32_e32 v4, 0x1000
	v_mov_b32_e32 v5, 1
	global_atomic_add v4, v4, v5, s[4:5] offset:1024 sc0
	s_sub_i32 s6, 4, s74
	s_waitcnt lgkmcnt(0)
	v_readfirstlane_b32 s7, v2
	v_readfirstlane_b32 s8, v3
	v_readfirstlane_b32 s9, v9
	s_mul_i32 s7, s7, s6
	s_add_i32 s6, s6, -1
	s_mul_i32 s8, s8, s6
	s_add_i32 s8, s8, 1
	v_mov_b32_e32 v6, 0x2000
	s_waitcnt vmcnt(0)
	v_readfirstlane_b32 s10, v4
	s_add_i32 s10, s10, 1
	s_cmp_lg_u32 s10, s7
	s_cbranch_scc1 .Lmy_fb_3_wait
	s_cmp_lg_u32 s9, 0
	s_cbranch_scc1 .Lmy_fb_3_nowb
	buffer_wbl2 sc1

; __device__ __forceinline__ unsigned xb_ld(unsigned* p)              { return __hip_atomic_load(p, __ATOMIC_RELAXED, __HIP_MEMORY_SCOPE_AGENT); }
; __device__ __forceinline__ unsigned xb_add(unsigned* p, unsigned v) { return __hip_atomic_fetch_add(p, v, __ATOMIC_RELAXED, __HIP_MEMORY_SCOPE_AGENT); }
; #define XB_SPIN(cond, bar) do { unsigned _sp = 0; while (cond) { __builtin_amdgcn_s_sleep(1); \
;     if ((++_sp & 255u) == 0u) { if (xb_ld(&(bar)[XB_TMO])) break; if (_sp > XB_SPIN_CAP) { atomicAdd(&(bar)[XB_TMO], 1u); break; } } } } while (0)
; __device__ __forceinline__ void xcd_barrier(const XcdBarrier& b) {
;     asm volatile("s_waitcnt vmcnt(0)" ::: "memory");
;     __syncthreads();
;     if (threadIdx.x == 0) {
;         unsigned* bar = b.bar;
;         __builtin_amdgcn_s_waitcnt(0);
;         unsigned nloc = b.st[0], nx = b.st[1];
;         if (nloc == 0u) { xcd_barrier_complete(bar, b.x, nloc, nx); b.st[0] = nloc; b.st[1] = nx; }
;         const unsigned old = xb_add(&bar[XB_XSUB(b.x)], 1u);
;         const unsigned gen = old / nloc;
;         if (old + 1u == (gen + 1u) * nloc) {
;             __builtin_amdgcn_fence(__ATOMIC_RELEASE, "agent");
;             asm volatile("s_waitcnt vmcnt(0)" ::: "memory");
;             const unsigned og = xb_add(&bar[XB_TOP], 1u);
;             const unsigned tg = og / nx;
;             if (og + 1u == (tg + 1u) * nx) xb_add(&bar[XB_TOPGEN], 1u);
;             else XB_SPIN(xb_ld(&bar[XB_TOPGEN]) == tg, bar);
;             __builtin_amdgcn_fence(__ATOMIC_ACQUIRE, "agent");
;             xb_add(&bar[XB_XGEN(b.x)], 1u);
;             asm volatile("s_waitcnt vmcnt(0)" ::: "memory");
;         } else {
;             XB_SPIN(xb_ld(&bar[XB_XGEN(b.x)]) == gen, bar);
;             __builtin_amdgcn_fence(__ATOMIC_ACQUIRE, "agent");
;             asm volatile("s_waitcnt vmcnt(0)" ::: "memory");
;         }
.Lmy_bpf_4:
	s_mov_b64 s[0:1], exec
	v_readlane_b32 s4, v254, 9
	v_readlane_b32 s5, v254, 10
	s_and_b64 s[4:5], s[0:1], s[4:5]
	s_mov_b64 exec, s[4:5]
	s_cbranch_execz .LBB0_958
	s_cmp_eq_u32 s74, 4
	s_cbranch_scc1 .Lmy_fb_4_orig
	s_add_i32 s4, 0, 0x26700
	v_mov_b32_e32 v0, s4
	ds_read2_b32 v[2:3], v0 offset1:1
	ds_read_b32 v9, v0 offset:8
	s_lshl_b32 s4, s88, 8
	s_add_u32 s4, s72, s4
	s_addc_u32 s5, s73, 0
	v_mov_b32_e32 v4, 0x1000
	v_mov_b32_e32 v5, 1
	global_atomic_add v4, v4, v5, s[4:5] offset:1024 sc0
	s_sub_i32 s6, 5, s74
	s_waitcnt lgkmcnt(0)
	v_readfirstlane_b32 s7, v2
	v_readfirstlane_b32 s8, v3
	v_readfirstlane_b32 s9, v9
	s_mul_i32 s7, s7, s6
	s_add_i32 s6, s6, -1
	s_mul_i32 s8, s8, s6
	s_add_i32 s8, s8, 1
	v_mov_b32_e32 v6, 0x2000
	s_waitcnt vmcnt(0)
	v_readfirstlane_b32 s10, v4
	s_add_i32 s10, s10, 1
	s_cmp_lg_u32 s10, s7
	s_cbranch_scc1 .Lmy_fb_4_wait
	s_cmp_lg_u32 s9, 0
	s_cbranch_scc1 .Lmy_fb_4_nowb
	buffer_wbl2 sc1

; __device__ __forceinline__ unsigned xb_ld(unsigned* p)              { return __hip_atomic_load(p, __ATOMIC_RELAXED, __HIP_MEMORY_SCOPE_AGENT); }
; __device__ __forceinline__ unsigned xb_add(unsigned* p, unsigned v) { return __hip_atomic_fetch_add(p, v, __ATOMIC_RELAXED, __HIP_MEMORY_SCOPE_AGENT); }
; #define XB_SPIN(cond, bar) do { unsigned _sp = 0; while (cond) { __builtin_amdgcn_s_sleep(1); \
;     if ((++_sp & 255u) == 0u) { if (xb_ld(&(bar)[XB_TMO])) break; if (_sp > XB_SPIN_CAP) { atomicAdd(&(bar)[XB_TMO], 1u); break; } } } } while (0)
; __device__ __forceinline__ void xcd_barrier(const XcdBarrier& b) {
;     asm volatile("s_waitcnt vmcnt(0)" ::: "memory");
;     __syncthreads();
;     if (threadIdx.x == 0) {
;         unsigned* bar = b.bar;
;         __builtin_amdgcn_s_waitcnt(0);
;         unsigned nloc = b.st[0], nx = b.st[1];
;         if (nloc == 0u) { xcd_barrier_complete(bar, b.x, nloc, nx); b.st[0] = nloc; b.st[1] = nx; }
;         const unsigned old = xb_add(&bar[XB_XSUB(b.x)], 1u);
;         const unsigned gen = old / nloc;
;         if (old + 1u == (gen + 1u) * nloc) {
;             __builtin_amdgcn_fence(__ATOMIC_RELEASE, "agent");
;             asm volatile("s_waitcnt vmcnt(0)" ::: "memory");
;             const unsigned og = xb_add(&bar[XB_TOP], 1u);
;             const unsigned tg = og / nx;
;             if (og + 1u == (tg + 1u) * nx) xb_add(&bar[XB_TOPGEN], 1u);
;             else XB_SPIN(xb_ld(&bar[XB_TOPGEN]) == tg, bar);
;             __builtin_amdgcn_fence(__ATOMIC_ACQUIRE, "agent");
;             xb_add(&bar[XB_XGEN(b.x)], 1u);
;             asm volatile("s_waitcnt vmcnt(0)" ::: "memory");
;         } else {
;             XB_SPIN(xb_ld(&bar[XB_XGEN(b.x)]) == gen, bar);
;             __builtin_amdgcn_fence(__ATOMIC_ACQUIRE, "agent");
;             asm volatile("s_waitcnt vmcnt(0)" ::: "memory");
;         }
.Lmy_bpf_5:
	s_mov_b64 s[0:1], exec
	v_readlane_b32 s4, v254, 9
	v_readlane_b32 s5, v254, 10
	s_and_b64 s[4:5], s[0:1], s[4:5]
	s_mov_b64 exec, s[4:5]
	s_cbranch_execz .LBB0_1029
	s_cmp_eq_u32 s74, 5
	s_cbranch_scc1 .Lmy_fb_5_orig
	s_add_i32 s4, 0, 0x26700
	v_mov_b32_e32 v0, s4
	ds_read2_b32 v[2:3], v0 offset1:1
	ds_read_b32 v9, v0 offset:8
	s_lshl_b32 s4, s88, 8
	s_add_u32 s4, s72, s4
	s_addc_u32 s5, s73, 0
	v_mov_b32_e32 v4, 0x1000
	v_mov_b32_e32 v5, 1
	global_atomic_add v4, v4, v5, s[4:5] offset:1024 sc0
	s_sub_i32 s6, 6, s74
	s_waitcnt lgkmcnt(0)
	v_readfirstlane_b32 s7, v2
	v_readfirstlane_b32 s8, v3
	v_readfirstlane_b32 s9, v9
	s_mul_i32 s7, s7, s6
	s_add_i32 s6, s6, -1
	s_mul_i32 s8, s8, s6
	s_add_i32 s8, s8, 1
	v_mov_b32_e32 v6, 0x2000
	s_waitcnt vmcnt(0)
	v_readfirstlane_b32 s10, v4
	s_add_i32 s10, s10, 1
	s_cmp_lg_u32 s10, s7
	s_cbranch_scc1 .Lmy_fb_5_wait
	s_cmp_lg_u32 s9, 0
	s_cbranch_scc1 .Lmy_fb_5_nowb
	buffer_wbl2 sc1
